# v76 + P13 sample rows + ada padding-row MFMAs removed + K-loop back-edge rotation + P6 sample recurrences hoisted (all four neutral edits together)
# speedup vs baseline: 1.0021x; 1.0011x over previous
; #define PG8_STAGE(bufoff, gbase, voff) do { _Pragma("unroll") for (int _i = 0; _i < 2; ++_i) \
;         __builtin_amdgcn_global_load_lds((const unsigned*)((const char*)(gbase) + (voff)[_i]), (LAS unsigned*)(lds + (bufoff) + ldsw + _i * 8192), 16, 0, 0); } while (0)
; #define PG8_LDA(dst, b, h) do { _Pragma("unroll") for (int m = 0; m < 4; ++m) _Pragma("unroll") for (int k = 0; k < 2; ++k) dst[m][k] = *(const LAS bf16x8*)(lds + PG8_SA(b, h) + aoff + m * 2048 + k * 1024); } while (0)
; #define PG8_LDB(dst, b, h) do { _Pragma("unroll") for (int n = 0; n < 2; ++n) _Pragma("unroll") for (int k = 0; k < 2; ++k) dst[n][k] = *(const LAS bf16x8*)(lds + PG8_SB(b, h) + boff + n * 2048 + k * 1024); } while (0)
; #define PG8_MMA(ai, bj, At, Bt) do { __builtin_amdgcn_s_setprio(1); _Pragma("unroll") for (int m = 0; m < 4; ++m) _Pragma("unroll") for (int n = 0; n < 2; ++n) _Pragma("unroll") for (int k = 0; k < 2; ++k) \
;         acc[ai][bj][m][n] = __builtin_amdgcn_mfma_f32_16x16x32_bf16(Bt[n][k], At[m][k], acc[ai][bj][m][n], 0, 0, 0); __builtin_amdgcn_s_setprio(0); } while (0)
; #define PG8_WAIT_V(n) asm volatile("s_waitcnt vmcnt(" #n ")" ::: "memory")
; #define PG8_WAIT_L(n) asm volatile("s_waitcnt lgkmcnt(" #n ")" ::: "memory")
; template <class Epi, class S_t>
; __device__ __forceinline__ void gemm_phase(LAS unsigned char* lds, int lda, int ldb, const S_t& S, const Epi& E) {
;     ...
;             PG8_LDB(B0, 0, 0); PG8_SCHED; PG8_LDA(At, 0, 0); PG8_STAGE(PG8_SA(1, 1), a1 + hstepA, voffA);
;             PG8_WAIT_L(8); PG8_BAR; PG8_WAIT_L(0); PG8_MMA(0, 0, At, B0); PG8_BAR; PG8_SCHED;
;             PG8_LDB(B1, 0, 1); PG8_STAGE(PG8_SB(0, 0), b2, voffB);
;             PG8_BAR; PG8_WAIT_L(0); PG8_MMA(0, 1, At, B1); PG8_BAR;
;             PG8_LDA(At, 0, 1); PG8_STAGE(PG8_SA(0, 0), a2, voffA);
;             PG8_BAR; PG8_WAIT_L(0); PG8_MMA(1, 0, At, B0); PG8_BAR; PG8_SCHED;
;             PG8_STAGE(PG8_SB(0, 1), b2 + hstepB, voffB);
;             PG8_WAIT_V(6); PG8_BAR; PG8_MMA(1, 1, At, B1); PG8_BAR;
;             PG8_LDB(B0, 1, 0); PG8_SCHED; PG8_LDA(At, 1, 0); PG8_STAGE(PG8_SA(0, 1), a2 + hstepA, voffA);
;             PG8_WAIT_L(8); PG8_BAR; PG8_WAIT_L(0); PG8_MMA(0, 0, At, B0); PG8_BAR; PG8_SCHED;
;             PG8_LDB(B1, 1, 1); PG8_STAGE(PG8_SB(1, 0), b3, voffB);
;             PG8_BAR; PG8_WAIT_L(0); PG8_MMA(0, 1, At, B1); PG8_BAR;
.LBB0_133:
	ds_read_b128 v[152:155], v175
	ds_read_b128 v[156:159], v175 offset:1024
	ds_read_b128 v[160:163], v175 offset:2048
	ds_read_b128 v[164:167], v175 offset:3072
	s_add_u32 s18, s16, 0xfff80080
	s_addc_u32 s19, s17, -1
	s_cmp_eq_u32 s9, 28
	s_cselect_b32 s21, s11, s19
	s_cselect_b32 s20, s10, s18
	s_cselect_b32 s19, s13, s1
	s_cselect_b32 s18, s12, s0
	s_add_i32 m0, s53, 0xc000
	ds_read_b128 v[186:189], v178
	ds_read_b128 v[190:193], v178 offset:1024
	ds_read_b128 v[194:197], v178 offset:2048
	ds_read_b128 v[198:201], v178 offset:3072
	ds_read_b128 v[202:205], v178 offset:4096
	ds_read_b128 v[206:209], v178 offset:5120
	ds_read_b128 v[214:217], v178 offset:6144
	ds_read_b128 v[218:221], v178 offset:7168
	global_load_lds_dwordx4 v148, s[16:17]
	s_add_i32 m0, s53, 0xe000
	s_nop 0
	global_load_lds_dwordx4 v150, s[16:17]
	s_waitcnt lgkmcnt(8)
	s_barrier
	s_waitcnt lgkmcnt(0)
	s_setprio 1
	v_mfma_f32_16x16x32_bf16 v[124:127], v[152:155], v[186:189], v[124:127]
	v_mfma_f32_16x16x32_bf16 v[92:95], v[160:163], v[186:189], v[92:95]
	v_mfma_f32_16x16x32_bf16 v[120:123], v[152:155], v[194:197], v[120:123]
	v_mfma_f32_16x16x32_bf16 v[88:91], v[160:163], v[194:197], v[88:91]
	v_mfma_f32_16x16x32_bf16 v[116:119], v[152:155], v[202:205], v[116:119]
	v_mfma_f32_16x16x32_bf16 v[84:87], v[160:163], v[202:205], v[84:87]
	v_mfma_f32_16x16x32_bf16 v[112:115], v[152:155], v[214:217], v[112:115]
	v_mfma_f32_16x16x32_bf16 v[80:83], v[160:163], v[214:217], v[80:83]
	v_mfma_f32_16x16x32_bf16 v[124:127], v[156:159], v[190:193], v[124:127]
	v_mfma_f32_16x16x32_bf16 v[92:95], v[164:167], v[190:193], v[92:95]
	v_mfma_f32_16x16x32_bf16 v[120:123], v[156:159], v[198:201], v[120:123]
	v_mfma_f32_16x16x32_bf16 v[88:91], v[164:167], v[198:201], v[88:91]
	v_mfma_f32_16x16x32_bf16 v[116:119], v[156:159], v[206:209], v[116:119]
	v_mfma_f32_16x16x32_bf16 v[84:87], v[164:167], v[206:209], v[84:87]
	v_mfma_f32_16x16x32_bf16 v[112:115], v[156:159], v[218:221], v[112:115]
	v_mfma_f32_16x16x32_bf16 v[80:83], v[164:167], v[218:221], v[80:83]
	s_setprio 0
	s_barrier
	s_add_i32 s33, s62, s43
	s_add_u32 s98, s18, s6
	s_addc_u32 s99, s19, s7
	s_mov_b32 m0, s33
	ds_read_b128 v[222:225], v179
	ds_read_b128 v[226:229], v179 offset:1024
	ds_read_b128 v[230:233], v179 offset:2048
	ds_read_b128 v[234:237], v179 offset:3072
	global_load_lds_dwordx4 v128, s[18:19]
	s_add_i32 m0, s33, 0x2000
	s_nop 0
	global_load_lds_dwordx4 v130, s[18:19]
	s_barrier
	s_waitcnt lgkmcnt(0)
	s_setprio 1
	v_mfma_f32_16x16x32_bf16 v[60:63], v[222:225], v[186:189], v[60:63]
	v_mfma_f32_16x16x32_bf16 v[28:31], v[230:233], v[186:189], v[28:31]
	v_mfma_f32_16x16x32_bf16 v[56:59], v[222:225], v[194:197], v[56:59]
	v_mfma_f32_16x16x32_bf16 v[24:27], v[230:233], v[194:197], v[24:27]
	v_mfma_f32_16x16x32_bf16 v[52:55], v[222:225], v[202:205], v[52:55]
	v_mfma_f32_16x16x32_bf16 v[20:23], v[230:233], v[202:205], v[20:23]
	v_mfma_f32_16x16x32_bf16 v[48:51], v[222:225], v[214:217], v[48:51]
	v_mfma_f32_16x16x32_bf16 v[16:19], v[230:233], v[214:217], v[16:19]
	v_mfma_f32_16x16x32_bf16 v[60:63], v[226:229], v[190:193], v[60:63]
	v_mfma_f32_16x16x32_bf16 v[28:31], v[234:237], v[190:193], v[28:31]
	v_mfma_f32_16x16x32_bf16 v[56:59], v[226:229], v[198:201], v[56:59]
	v_mfma_f32_16x16x32_bf16 v[24:27], v[234:237], v[198:201], v[24:27]
	v_mfma_f32_16x16x32_bf16 v[52:55], v[226:229], v[206:209], v[52:55]
	v_mfma_f32_16x16x32_bf16 v[20:23], v[234:237], v[206:209], v[20:23]
	v_mfma_f32_16x16x32_bf16 v[48:51], v[226:229], v[218:221], v[48:51]
	v_mfma_f32_16x16x32_bf16 v[16:19], v[234:237], v[218:221], v[16:19]
	s_setprio 0
	s_mov_b32 m0, s53
	s_add_u32 s100, s20, s6
	s_addc_u32 s101, s21, s7
	s_barrier
	ds_read_b128 v[186:189], v178 offset:16384
	ds_read_b128 v[190:193], v178 offset:17408
	ds_read_b128 v[194:197], v178 offset:18432
	ds_read_b128 v[198:201], v178 offset:19456
	ds_read_b128 v[202:205], v178 offset:20480
	ds_read_b128 v[206:209], v178 offset:21504
	ds_read_b128 v[214:217], v178 offset:22528
	ds_read_b128 v[218:221], v178 offset:23552
	global_load_lds_dwordx4 v128, s[20:21]
	s_mov_b32 m0, s54
	s_nop 0
	global_load_lds_dwordx4 v130, s[20:21]
	s_barrier
	s_waitcnt lgkmcnt(0)
	s_setprio 1
	v_mfma_f32_16x16x32_bf16 v[108:111], v[152:155], v[186:189], v[108:111]
	v_mfma_f32_16x16x32_bf16 v[76:79], v[160:163], v[186:189], v[76:79]
	v_mfma_f32_16x16x32_bf16 v[108:111], v[156:159], v[190:193], v[108:111]
	v_mfma_f32_16x16x32_bf16 v[76:79], v[164:167], v[190:193], v[76:79]
	s_setprio 0
	s_barrier
	s_add_u32 s66, s18, 0x80000
	s_addc_u32 s67, s19, 0
	s_add_i32 s33, s63, s43
	s_mov_b32 m0, s33
	s_nop 0
	global_load_lds_dwordx4 v128, s[66:67]
	s_add_i32 m0, s33, 0x2000
	s_nop 0
	global_load_lds_dwordx4 v130, s[66:67]
	s_waitcnt vmcnt(6)
	s_barrier
	s_setprio 1
	v_mfma_f32_16x16x32_bf16 v[44:47], v[222:225], v[186:189], v[44:47]
	v_mfma_f32_16x16x32_bf16 v[12:15], v[230:233], v[186:189], v[12:15]
	v_mfma_f32_16x16x32_bf16 v[44:47], v[226:229], v[190:193], v[44:47]
	v_mfma_f32_16x16x32_bf16 v[12:15], v[234:237], v[190:193], v[12:15]
	s_setprio 0
	s_add_i32 s33, 0, 0x18000
	v_add_u32_e32 v164, s33, v171
	s_barrier
	ds_read_b128 v[152:155], v164
	ds_read_b128 v[156:159], v164 offset:1024
	ds_read_b128 v[160:163], v164 offset:2048
	ds_read_b128 v[164:167], v164 offset:3072
	s_add_u32 s20, s20, 0x80000
	s_addc_u32 s21, s21, 0
	s_mov_b32 m0, s55
	ds_read_b128 v[186:189], v178 offset:32768
	ds_read_b128 v[190:193], v178 offset:33792
	ds_read_b128 v[194:197], v178 offset:34816
	ds_read_b128 v[198:201], v178 offset:35840
	ds_read_b128 v[202:205], v178 offset:36864
	ds_read_b128 v[206:209], v178 offset:37888
	ds_read_b128 v[214:217], v178 offset:38912
	ds_read_b128 v[218:221], v178 offset:39936
	global_load_lds_dwordx4 v128, s[20:21]
	s_mov_b32 m0, s56
	s_nop 0
	global_load_lds_dwordx4 v130, s[20:21]
	s_waitcnt lgkmcnt(8)
	s_barrier
; #define PG8_STAGE(bufoff, gbase, voff) do { _Pragma("unroll") for (int _i = 0; _i < 2; ++_i) \
;         __builtin_amdgcn_global_load_lds((const unsigned*)((const char*)(gbase) + (voff)[_i]), (LAS unsigned*)(lds + (bufoff) + ldsw + _i * 8192), 16, 0, 0); } while (0)
; #define PG8_LDA(dst, b, h) do { _Pragma("unroll") for (int m = 0; m < 4; ++m) _Pragma("unroll") for (int k = 0; k < 2; ++k) dst[m][k] = *(const LAS bf16x8*)(lds + PG8_SA(b, h) + aoff + m * 2048 + k * 1024); } while (0)
; #define PG8_LDB(dst, b, h) do { _Pragma("unroll") for (int n = 0; n < 2; ++n) _Pragma("unroll") for (int k = 0; k < 2; ++k) dst[n][k] = *(const LAS bf16x8*)(lds + PG8_SB(b, h) + boff + n * 2048 + k * 1024); } while (0)
; #define PG8_MMA(ai, bj, At, Bt) do { __builtin_amdgcn_s_setprio(1); _Pragma("unroll") for (int m = 0; m < 4; ++m) _Pragma("unroll") for (int n = 0; n < 2; ++n) _Pragma("unroll") for (int k = 0; k < 2; ++k) \
;         acc[ai][bj][m][n] = __builtin_amdgcn_mfma_f32_16x16x32_bf16(Bt[n][k], At[m][k], acc[ai][bj][m][n], 0, 0, 0); __builtin_amdgcn_s_setprio(0); } while (0)
; #define PG8_WAIT_V(n) asm volatile("s_waitcnt vmcnt(" #n ")" ::: "memory")
; template <class Epi, class S_t>
; __device__ __forceinline__ void gemm_phase(LAS unsigned char* lds, int lda, int ldb, const S_t& S, const Epi& E) {
;     ...
;             PG8_LDB(B0, 1, 0); PG8_SCHED; PG8_LDA(At, 1, 0); PG8_STAGE(PG8_SA(0, 1), a2 + hstepA, voffA);
;             PG8_WAIT_L(8); PG8_BAR; PG8_WAIT_L(0); PG8_MMA(0, 0, At, B0); PG8_BAR; PG8_SCHED;
;             PG8_LDB(B1, 1, 1); PG8_STAGE(PG8_SB(1, 0), b3, voffB);
;             PG8_BAR; PG8_WAIT_L(0); PG8_MMA(0, 1, At, B1); PG8_BAR;
;             PG8_LDA(At, 1, 1); PG8_STAGE(PG8_SA(1, 0), a3, voffA);
;             PG8_BAR; PG8_WAIT_L(0); PG8_MMA(1, 0, At, B0); PG8_BAR; PG8_SCHED;
;             PG8_STAGE(PG8_SB(1, 1), b3 + hstepB, voffB);
;             PG8_WAIT_V(6); PG8_BAR; PG8_MMA(1, 1, At, B1); PG8_BAR;
;     __device__ __forceinline__ void operator()(const f32x4 (&acc)[2][2][4][2], const Unit& u, int wr, int wc, int fr, int fq) const {
;         const int row0 = wr * 64 + fr, col0 = u.pn * BM + wc * 32 + 4 * fq, kind = u.pn >> 3;
;         const float* gm = kind == 2 ? g2 : kind == 4 ? g4 : kind == 5 ? g5 : g1;
;         const float one = (kind == 1 || kind == 4) ? 1.0f : 0.0f, gs = (kind == 0 || kind == 3) ? 0.0f : 1.0f;
	s_waitcnt lgkmcnt(0)
	s_setprio 1
	v_mfma_f32_16x16x32_bf16 v[124:127], v[152:155], v[186:189], v[124:127]
	v_mfma_f32_16x16x32_bf16 v[92:95], v[160:163], v[186:189], v[92:95]
	v_mfma_f32_16x16x32_bf16 v[120:123], v[152:155], v[194:197], v[120:123]
	v_mfma_f32_16x16x32_bf16 v[88:91], v[160:163], v[194:197], v[88:91]
	v_mfma_f32_16x16x32_bf16 v[116:119], v[152:155], v[202:205], v[116:119]
	v_mfma_f32_16x16x32_bf16 v[84:87], v[160:163], v[202:205], v[84:87]
	v_mfma_f32_16x16x32_bf16 v[112:115], v[152:155], v[214:217], v[112:115]
	v_mfma_f32_16x16x32_bf16 v[80:83], v[160:163], v[214:217], v[80:83]
	v_mfma_f32_16x16x32_bf16 v[124:127], v[156:159], v[190:193], v[124:127]
	v_mfma_f32_16x16x32_bf16 v[92:95], v[164:167], v[190:193], v[92:95]
	v_mfma_f32_16x16x32_bf16 v[120:123], v[156:159], v[198:201], v[120:123]
	v_mfma_f32_16x16x32_bf16 v[88:91], v[164:167], v[198:201], v[88:91]
	v_mfma_f32_16x16x32_bf16 v[116:119], v[156:159], v[206:209], v[116:119]
	v_mfma_f32_16x16x32_bf16 v[84:87], v[164:167], v[206:209], v[84:87]
	v_mfma_f32_16x16x32_bf16 v[112:115], v[156:159], v[218:221], v[112:115]
	v_mfma_f32_16x16x32_bf16 v[80:83], v[164:167], v[218:221], v[80:83]
	s_setprio 0
	s_barrier
	s_add_i32 s20, 0, 0x1c000
	s_add_i32 s21, s33, s43
	v_add_u32_e32 v170, s20, v171
	s_mov_b32 m0, s21
	ds_read_b128 v[222:225], v170
	ds_read_b128 v[226:229], v170 offset:1024
	ds_read_b128 v[230:233], v170 offset:2048
	ds_read_b128 v[234:237], v170 offset:3072
	global_load_lds_dwordx4 v128, s[98:99]
	s_add_i32 m0, s21, 0x2000
	s_nop 0
	global_load_lds_dwordx4 v130, s[98:99]
	s_barrier
	s_waitcnt lgkmcnt(0)
	s_setprio 1
	v_mfma_f32_16x16x32_bf16 v[60:63], v[222:225], v[186:189], v[60:63]
	v_mfma_f32_16x16x32_bf16 v[28:31], v[230:233], v[186:189], v[28:31]
	v_mfma_f32_16x16x32_bf16 v[56:59], v[222:225], v[194:197], v[56:59]
	v_mfma_f32_16x16x32_bf16 v[24:27], v[230:233], v[194:197], v[24:27]
	v_mfma_f32_16x16x32_bf16 v[52:55], v[222:225], v[202:205], v[52:55]
	v_mfma_f32_16x16x32_bf16 v[20:23], v[230:233], v[202:205], v[20:23]
	v_mfma_f32_16x16x32_bf16 v[48:51], v[222:225], v[214:217], v[48:51]
	v_mfma_f32_16x16x32_bf16 v[16:19], v[230:233], v[214:217], v[16:19]
	v_mfma_f32_16x16x32_bf16 v[60:63], v[226:229], v[190:193], v[60:63]
	v_mfma_f32_16x16x32_bf16 v[28:31], v[234:237], v[190:193], v[28:31]
	v_mfma_f32_16x16x32_bf16 v[56:59], v[226:229], v[198:201], v[56:59]
	v_mfma_f32_16x16x32_bf16 v[24:27], v[234:237], v[198:201], v[24:27]
	v_mfma_f32_16x16x32_bf16 v[52:55], v[226:229], v[206:209], v[52:55]
	v_mfma_f32_16x16x32_bf16 v[20:23], v[234:237], v[206:209], v[20:23]
	v_mfma_f32_16x16x32_bf16 v[48:51], v[226:229], v[218:221], v[48:51]
	v_mfma_f32_16x16x32_bf16 v[16:19], v[234:237], v[218:221], v[16:19]
	s_setprio 0
	s_mov_b32 m0, s58
	s_barrier
	ds_read_b128 v[186:189], v178 offset:49152
	ds_read_b128 v[190:193], v178 offset:50176
	ds_read_b128 v[194:197], v178 offset:51200
	ds_read_b128 v[198:201], v178 offset:52224
	ds_read_b128 v[202:205], v178 offset:53248
	ds_read_b128 v[206:209], v178 offset:54272
	ds_read_b128 v[214:217], v178 offset:55296
	ds_read_b128 v[218:221], v178 offset:56320
	global_load_lds_dwordx4 v128, s[100:101]
	s_mov_b32 m0, s59
	s_nop 0
	global_load_lds_dwordx4 v130, s[100:101]
	s_barrier
	s_waitcnt lgkmcnt(0)
	s_setprio 1
	v_mfma_f32_16x16x32_bf16 v[108:111], v[152:155], v[186:189], v[108:111]
	v_mfma_f32_16x16x32_bf16 v[76:79], v[160:163], v[186:189], v[76:79]
	v_mfma_f32_16x16x32_bf16 v[108:111], v[156:159], v[190:193], v[108:111]
	v_mfma_f32_16x16x32_bf16 v[76:79], v[164:167], v[190:193], v[76:79]
	s_setprio 0
	s_barrier
	s_add_u32 s18, s18, 0x80080
	s_addc_u32 s19, s19, 0
	s_add_i32 s20, s20, s43
	s_mov_b32 m0, s20
	s_nop 0
	global_load_lds_dwordx4 v128, s[18:19]
	s_add_i32 m0, s20, 0x2000
	s_nop 0
	global_load_lds_dwordx4 v130, s[18:19]
	s_waitcnt vmcnt(6)
	s_barrier
	s_setprio 1
	v_mfma_f32_16x16x32_bf16 v[44:47], v[222:225], v[186:189], v[44:47]
	v_mfma_f32_16x16x32_bf16 v[12:15], v[230:233], v[186:189], v[12:15]
	v_mfma_f32_16x16x32_bf16 v[44:47], v[226:229], v[190:193], v[44:47]
	v_mfma_f32_16x16x32_bf16 v[12:15], v[234:237], v[190:193], v[12:15]
	s_setprio 0
	s_add_i32 s9, s9, 2
	s_add_u32 s16, s16, 0x100
	s_addc_u32 s17, s17, 0
	s_add_u32 s0, s0, 0x100
	s_addc_u32 s1, s1, 0
	s_cmp_gt_u32 s9, 29
	s_cbranch_scc0 .Lrot_133
	s_barrier
	s_ashr_i32 s9, s64, 3
	s_cmp_lt_i32 s9, 4
	s_cbranch_scc1 .LBB0_138
	v_readlane_b32 s68, v254, 17
	v_readlane_b32 s76, v254, 25
	v_readlane_b32 s77, v254, 26
	s_cmp_gt_i32 s9, 4
	s_mov_b64 s[18:19], 0
	s_mov_b64 s[16:17], s[76:77]
	s_mov_b64 s[0:1], 0
	v_readlane_b32 s69, v254, 18
	v_readlane_b32 s70, v254, 19
	v_readlane_b32 s71, v254, 20
	v_readlane_b32 s72, v254, 21
	v_readlane_b32 s73, v254, 22
	v_readlane_b32 s74, v254, 23
	v_readlane_b32 s75, v254, 24
	v_readlane_b32 s78, v254, 27
	v_readlane_b32 s79, v254, 28
	v_readlane_b32 s80, v254, 29
	v_readlane_b32 s81, v254, 30
	v_readlane_b32 s82, v254, 31
	v_readlane_b32 s83, v254, 32
	s_cbranch_scc0 .LBB0_139
	s_cmp_eq_u32 s9, 5
	s_mov_b64 s[0:1], -1
	s_cbranch_scc0 .LBB0_139
	v_readlane_b32 s68, v254, 17
	v_readlane_b32 s78, v254, 27
	v_readlane_b32 s79, v254, 28
	s_mov_b64 s[0:1], 0
	v_readlane_b32 s69, v254, 18
	v_readlane_b32 s70, v254, 19
	v_readlane_b32 s71, v254, 20
	v_readlane_b32 s72, v254, 21
	v_readlane_b32 s73, v254, 22
	v_readlane_b32 s74, v254, 23
	v_readlane_b32 s75, v254, 24
	v_readlane_b32 s76, v254, 25
	v_readlane_b32 s77, v254, 26
	v_readlane_b32 s80, v254, 29
	v_readlane_b32 s81, v254, 30
	v_readlane_b32 s82, v254, 31
	v_readlane_b32 s83, v254, 32
	s_mov_b64 s[16:17], s[78:79]
	s_branch .LBB0_139
